# sel loop: per-lane tile-selected bit taken from a rolling copy of the selection mask (one alignbit shift pair per iteration) instead of variable shifts + select per step
# baseline (speedup 1.0000x reference)
.LBB0_1147:
	v_lshlrev_b32_e32 v34, 12, v225
	v_add3_u32 v109, s77, v34, v38
	v_lshl_add_u32 v34, v226, 3, 0
	v_add_u32_e32 v34, 0x20000, v34
	v_pk_mul_f32 v[2:3], v[0:1], v[2:3] op_sel_hi:[0,1]
	s_waitcnt lgkmcnt(0)
	s_barrier
	ds_read_b64 v[102:103], v34
	v_cvt_pk_bf16_f32 v34, v2, v3
	v_pk_mul_f32 v[2:3], v[0:1], v[18:19] op_sel_hi:[0,1]
	v_cvt_pk_bf16_f32 v18, v2, v3
	v_pk_mul_f32 v[2:3], v[0:1], v[4:5] op_sel_hi:[0,1]
	v_cvt_pk_bf16_f32 v2, v2, v3
	ds_write2st64_b32 v109, v34, v2 offset1:1
	v_pk_mul_f32 v[2:3], v[0:1], v[20:21] op_sel_hi:[0,1]
	v_cvt_pk_bf16_f32 v2, v2, v3
	ds_write2st64_b32 v109, v18, v2 offset0:8 offset1:9
	v_pk_mul_f32 v[2:3], v[0:1], v[6:7] op_sel_hi:[0,1]
	v_cvt_pk_bf16_f32 v4, v2, v3
	v_pk_mul_f32 v[2:3], v[0:1], v[22:23] op_sel_hi:[0,1]
	v_cvt_pk_bf16_f32 v5, v2, v3
	v_pk_mul_f32 v[2:3], v[0:1], v[8:9] op_sel_hi:[0,1]
	v_cvt_pk_bf16_f32 v2, v2, v3
	ds_write2st64_b32 v109, v4, v2 offset0:2 offset1:3
	v_pk_mul_f32 v[2:3], v[0:1], v[24:25] op_sel_hi:[0,1]
	v_cvt_pk_bf16_f32 v2, v2, v3
	ds_write2st64_b32 v109, v5, v2 offset0:10 offset1:11
	v_pk_mul_f32 v[2:3], v[0:1], v[10:11] op_sel_hi:[0,1]
	v_cvt_pk_bf16_f32 v4, v2, v3
	v_pk_mul_f32 v[2:3], v[0:1], v[26:27] op_sel_hi:[0,1]
	v_cvt_pk_bf16_f32 v5, v2, v3
	v_pk_mul_f32 v[2:3], v[0:1], v[12:13] op_sel_hi:[0,1]
	v_cvt_pk_bf16_f32 v2, v2, v3
	ds_write2st64_b32 v109, v4, v2 offset0:4 offset1:5
	v_pk_mul_f32 v[2:3], v[0:1], v[28:29] op_sel_hi:[0,1]
	s_lshl_b32 s0, s64, 19
	v_readlane_b32 s4, v252, 7
	v_cvt_pk_bf16_f32 v2, v2, v3
	v_readlane_b32 s5, v252, 8
	s_add_u32 s0, s4, s0
	ds_write2st64_b32 v109, v5, v2 offset0:12 offset1:13
	v_pk_mul_f32 v[2:3], v[0:1], v[14:15] op_sel_hi:[0,1]
	s_addc_u32 s1, s5, 0
	v_cvt_pk_bf16_f32 v4, v2, v3
	v_pk_mul_f32 v[2:3], v[0:1], v[30:31] op_sel_hi:[0,1]
	v_lshl_add_u64 v[98:99], v[186:187], 1, s[0:1]
	v_lshl_add_u64 v[100:101], v[188:189], 1, s[0:1]
	s_mov_b64 s[0:1], 0x1800000
	v_cvt_pk_bf16_f32 v5, v2, v3
	v_pk_mul_f32 v[2:3], v[0:1], v[16:17] op_sel_hi:[0,1]
	v_lshl_add_u64 v[106:107], v[100:101], 0, s[0:1]
	s_min_i32 s0, s68, 0
	v_cvt_pk_bf16_f32 v2, v2, v3
	s_mov_b64 s[2:3], 0x1000000
	s_ashr_i32 s1, s0, 31
	ds_write2st64_b32 v109, v4, v2 offset0:6 offset1:7
	v_pk_mul_f32 v[2:3], v[0:1], v[32:33] op_sel_hi:[0,1]
	v_lshl_add_u64 v[104:105], v[98:99], 0, s[2:3]
	s_lshl_b64 s[0:1], s[0:1], 13
	v_readfirstlane_b32 s2, v200
	v_cvt_pk_bf16_f32 v0, v2, v3
	v_lshl_add_u64 v[2:3], v[104:105], 0, s[0:1]
	s_mov_b32 m0, s2
	ds_write2st64_b32 v109, v5, v0 offset0:14 offset1:15
	global_load_lds_dwordx4 v[2:3], off
	v_lshl_add_u64 v[2:3], v[106:107], 0, s[0:1]
	v_readfirstlane_b32 s0, v213
	s_mov_b32 m0, s0
	s_min_i32 s0, s68, 1
	s_ashr_i32 s1, s0, 31
	s_lshl_b64 s[0:1], s[0:1], 13
	v_readfirstlane_b32 s2, v214
	global_load_lds_dwordx4 v[2:3], off
	v_lshl_add_u64 v[2:3], v[104:105], 0, s[0:1]
	s_mov_b32 m0, s2
	v_readfirstlane_b32 s2, v216
	global_load_lds_dwordx4 v[2:3], off
	v_lshl_add_u64 v[2:3], v[106:107], 0, s[0:1]
	v_readfirstlane_b32 s0, v215
	s_mov_b32 m0, s0
	s_min_i32 s0, s68, 2
	s_ashr_i32 s1, s0, 31
	s_lshl_b64 s[0:1], s[0:1], 13
	global_load_lds_dwordx4 v[2:3], off
	v_lshl_add_u64 v[2:3], v[104:105], 0, s[0:1]
	s_mov_b32 m0, s2
	v_readfirstlane_b32 s2, v218
	global_load_lds_dwordx4 v[2:3], off
	v_lshl_add_u64 v[2:3], v[106:107], 0, s[0:1]
	v_readfirstlane_b32 s0, v217
	s_mov_b32 m0, s0
	s_min_i32 s0, s68, 3
	s_ashr_i32 s1, s0, 31
	s_lshl_b64 s[0:1], s[0:1], 13
	global_load_lds_dwordx4 v[2:3], off
	v_lshl_add_u64 v[2:3], v[104:105], 0, s[0:1]
	s_mov_b32 m0, s2
	v_add_u32_e32 v113, s76, v224
	global_load_lds_dwordx4 v[2:3], off
	v_lshl_add_u64 v[2:3], v[106:107], 0, s[0:1]
	v_readfirstlane_b32 s0, v221
	s_mov_b32 m0, s0
	s_min_i32 s0, s68, 4
	s_ashr_i32 s1, s0, 31
	s_lshl_b64 s[0:1], s[0:1], 13
	v_readfirstlane_b32 s2, v113
	global_load_lds_dwordx4 v[2:3], off
	v_lshl_add_u64 v[2:3], v[104:105], 0, s[0:1]
	s_mov_b32 m0, s2
	v_add_u32_e32 v114, s78, v224
	global_load_lds_dwordx4 v[2:3], off
	v_lshl_add_u64 v[2:3], v[106:107], 0, s[0:1]
	v_readfirstlane_b32 s0, v114
	s_mov_b32 m0, s0
	v_lshlrev_b32_e32 v0, 8, v199
	global_load_lds_dwordx4 v[2:3], off
	s_waitcnt vmcnt(8)
	s_barrier
	ds_read_b128 v[2:5], v222
	ds_read_b128 v[6:9], v222 offset:4096
	s_waitcnt lgkmcnt(0)
	v_mfma_f32_32x32x16_bf16 v[34:49], v[2:5], v[162:165], 0
	s_mov_b32 s42, 0
	s_cmp_lt_i32 s74, 64
	s_nop 4
	v_mfma_f32_32x32x16_bf16 v[50:65], v[6:9], v[162:165], 0
	ds_read_b128 v[2:5], v219
	ds_read_b128 v[6:9], v219 offset:4096
	s_nop 0
	v_readlane_b32 s12, v252, 15
	v_readlane_b32 s13, v252, 16
	s_nop 1
	v_readlane_b32 s16, v252, 19
	s_waitcnt lgkmcnt(0)
	v_mfma_f32_32x32x16_bf16 v[34:49], v[2:5], v[166:169], v[34:49]
	v_readlane_b32 s17, v252, 20
	v_readlane_b32 s18, v252, 21
	v_readlane_b32 s19, v252, 22
	v_mfma_f32_32x32x16_bf16 v[50:65], v[6:9], v[166:169], v[50:65]
	ds_read_b128 v[2:5], v212
	ds_read_b128 v[6:9], v212 offset:4096
	s_waitcnt lgkmcnt(0)
	v_mfma_f32_32x32x16_bf16 v[34:49], v[2:5], v[170:173], v[34:49]
	v_mfma_f32_32x32x16_bf16 v[50:65], v[6:9], v[170:173], v[50:65]
	ds_read_b128 v[2:5], v211
	ds_read_b128 v[6:9], v211 offset:4096
	s_waitcnt lgkmcnt(0)
	v_mfma_f32_32x32x16_bf16 v[34:49], v[2:5], v[174:177], v[34:49]
	v_and_b32_e32 v2, 0xc0, v224
	v_add3_u32 v0, 0, v0, v2
	v_add3_u32 v112, v0, v229, v228
	v_mfma_f32_32x32x16_bf16 v[50:65], v[6:9], v[174:177], v[50:65]
	s_cbranch_scc0 .LBB0_1176
	v_mov_b32_e32 v2, v1
	v_mov_b32_e32 v3, v1
	v_mov_b32_e32 v4, v1
	v_mov_b32_e32 v5, v1
	v_mov_b32_e32 v6, v1
	v_mov_b32_e32 v7, v1
	v_mov_b32_e32 v8, v1
	v_mov_b32_e32 v9, v1
	v_mov_b32_e32 v10, v1
	v_mov_b32_e32 v11, v1
	v_mov_b32_e32 v12, v1
	v_mov_b32_e32 v13, v1
	v_mov_b32_e32 v14, v1
	v_mov_b32_e32 v15, v1
	v_mov_b32_e32 v16, v1
	v_mov_b32_e32 v17, v1
	v_mov_b32_e32 v18, v1
	v_mov_b32_e32 v19, v1
	v_mov_b32_e32 v20, v1
	v_mov_b32_e32 v21, v1
	v_mov_b32_e32 v22, v1
	v_mov_b32_e32 v23, v1
	v_mov_b32_e32 v24, v1
	v_mov_b32_e32 v25, v1
	v_mov_b32_e32 v26, v1
	v_mov_b32_e32 v27, v1
	v_mov_b32_e32 v28, v1
	v_mov_b32_e32 v29, v1
	v_mov_b32_e32 v30, v1
	v_mov_b32_e32 v31, v1
	v_mov_b32_e32 v0, v1
	v_mov_b64_e32 v[32:33], v[30:31]
	v_cmp_gt_i32_e64 s[0:1], 0, v184
	s_mov_b32 s43, 5
	s_mov_b64 s[38:39], -1
	v_mov_b32_e32 v115, 0
	v_mov_b32_e32 v116, 0xf149f2ca
	s_movk_i32 s44, 0x7f
	v_mov_b64_e32 v[30:31], v[28:29]
	v_mov_b64_e32 v[28:29], v[26:27]
	v_mov_b64_e32 v[26:27], v[24:25]
	v_mov_b64_e32 v[24:25], v[22:23]
	v_mov_b64_e32 v[22:23], v[20:21]
	v_mov_b64_e32 v[20:21], v[18:19]
	v_mov_b64_e32 v[18:19], v[16:17]
	v_mov_b64_e32 v[16:17], v[14:15]
	v_mov_b64_e32 v[14:15], v[12:13]
	v_mov_b64_e32 v[12:13], v[10:11]
	v_mov_b64_e32 v[10:11], v[8:9]
	v_mov_b64_e32 v[8:9], v[6:7]
	v_mov_b64_e32 v[6:7], v[4:5]
	v_mov_b64_e32 v[4:5], v[2:3]
	v_mov_b64_e32 v[2:3], v[0:1]
	s_mov_b32 s45, 0
	s_waitcnt lgkmcnt(0)
	v_mov_b32_e32 v238, v102
	v_mov_b32_e32 v239, v103
	s_nop 1
	v_or_b32_dpp v238, v238, v238 quad_perm:[1,0,3,2] row_mask:0xf bank_mask:0xf
	v_or_b32_dpp v239, v239, v239 quad_perm:[1,0,3,2] row_mask:0xf bank_mask:0xf
	s_nop 1
	v_or_b32_dpp v238, v238, v238 quad_perm:[2,3,0,1] row_mask:0xf bank_mask:0xf
	v_or_b32_dpp v239, v239, v239 quad_perm:[2,3,0,1] row_mask:0xf bank_mask:0xf
	s_nop 1
	v_or_b32_dpp v238, v238, v238 row_half_mirror row_mask:0xf bank_mask:0xf
	v_or_b32_dpp v239, v239, v239 row_half_mirror row_mask:0xf bank_mask:0xf
	s_nop 1
	v_or_b32_dpp v238, v238, v238 row_mirror row_mask:0xf bank_mask:0xf
	v_or_b32_dpp v239, v239, v239 row_mirror row_mask:0xf bank_mask:0xf
	s_nop 1
	v_readlane_b32 s100, v238, 0
	v_readlane_b32 s2, v238, 16
	v_readlane_b32 s3, v238, 32
	v_readlane_b32 s101, v238, 48
	s_or_b32 s100, s100, s2
	s_or_b32 s3, s3, s101
	s_or_b32 s100, s100, s3
	v_readlane_b32 s101, v239, 0
	v_readlane_b32 s2, v239, 16
	v_readlane_b32 s3, v239, 32
	s_or_b32 s101, s101, s2
	v_readlane_b32 s2, v239, 48
	s_or_b32 s101, s101, s3
	s_or_b32 s101, s101, s2
	v_mov_b32_e32 v240, v102
	v_mov_b32_e32 v241, v103
	s_branch .LBB0_1150
.LBB0_1149:
	s_mov_b32 s45, s46
	v_mov_b32_e32 v116, v117
	s_add_i32 s42, s42, 2
	v_alignbit_b32 v240, v241, v240, 2
	v_lshrrev_b32_e32 v241, 2, v241
	s_addk_i32 s44, 0x80
	s_cmp_le_i32 s42, s68
	s_cbranch_scc0 .LBB0_1177

.LBB0_1158:
	v_max_f32_e32 v108, v34, v35
	v_max3_f32 v108, v108, v36, v37
	v_max3_f32 v108, v108, v38, v39
	v_max3_f32 v108, v108, v40, v41
	v_max3_f32 v108, v108, v42, v43
	v_max3_f32 v108, v108, v44, v45
	v_max3_f32 v108, v108, v46, v47
	v_max3_f32 v108, v108, v48, v49
	v_max3_f32 v108, v108, v50, v51
	v_max3_f32 v108, v108, v52, v53
	v_max3_f32 v108, v108, v54, v55
	v_max3_f32 v108, v108, v56, v57
	v_max3_f32 v108, v108, v58, v59
	v_max3_f32 v108, v108, v60, v61
	v_max3_f32 v108, v108, v62, v63
	v_max3_f32 v108, v108, v64, v65
	ds_bpermute_b32 v110, v209, v108
	v_and_b32_e32 v0, 1, v240
	s_waitcnt lgkmcnt(0)
	v_max_f32_e32 v108, v108, v110
	v_cmp_eq_u32_e64 s[2:3], 0, v0
	s_nop 1
	v_cndmask_b32_e64 v0, v108, v196, s[2:3]
	v_max_f32_e32 v117, v116, v0
	v_sub_f32_e32 v0, v116, v117
	v_exp_f32_e32 v108, v0
	s_nop 0
	v_cmp_neq_f32_e32 vcc, 1.0, v108
	s_cbranch_vccz .LBB0_1160
	v_pk_mul_f32 v[32:33], v[32:33], v[108:109] op_sel_hi:[1,0]
	v_pk_mul_f32 v[30:31], v[30:31], v[108:109] op_sel_hi:[1,0]
	v_pk_mul_f32 v[28:29], v[28:29], v[108:109] op_sel_hi:[1,0]
	v_pk_mul_f32 v[26:27], v[26:27], v[108:109] op_sel_hi:[1,0]
	v_pk_mul_f32 v[24:25], v[24:25], v[108:109] op_sel_hi:[1,0]
	v_pk_mul_f32 v[22:23], v[22:23], v[108:109] op_sel_hi:[1,0]
	v_pk_mul_f32 v[20:21], v[20:21], v[108:109] op_sel_hi:[1,0]
	v_pk_mul_f32 v[18:19], v[18:19], v[108:109] op_sel_hi:[1,0]
	v_pk_mul_f32 v[16:17], v[16:17], v[108:109] op_sel_hi:[1,0]
	v_pk_mul_f32 v[14:15], v[14:15], v[108:109] op_sel_hi:[1,0]
	v_pk_mul_f32 v[12:13], v[12:13], v[108:109] op_sel_hi:[1,0]
	v_pk_mul_f32 v[10:11], v[10:11], v[108:109] op_sel_hi:[1,0]
	v_pk_mul_f32 v[8:9], v[8:9], v[108:109] op_sel_hi:[1,0]
	v_pk_mul_f32 v[6:7], v[6:7], v[108:109] op_sel_hi:[1,0]
	v_pk_mul_f32 v[4:5], v[4:5], v[108:109] op_sel_hi:[1,0]
	v_pk_mul_f32 v[2:3], v[2:3], v[108:109] op_sel_hi:[1,0]

.LBB0_1171:
	v_max_f32_e32 v108, v66, v67
	v_max3_f32 v108, v108, v68, v69
	v_max3_f32 v108, v108, v70, v71
	v_max3_f32 v108, v108, v72, v73
	v_max3_f32 v108, v108, v74, v75
	v_max3_f32 v108, v108, v76, v77
	v_max3_f32 v108, v108, v78, v79
	v_max3_f32 v108, v108, v80, v81
	v_max3_f32 v108, v108, v82, v83
	v_max3_f32 v108, v108, v84, v85
	v_max3_f32 v108, v108, v86, v87
	v_max3_f32 v108, v108, v88, v89
	v_max3_f32 v108, v108, v90, v91
	v_max3_f32 v108, v108, v92, v93
	v_max3_f32 v108, v108, v94, v95
	v_max3_f32 v108, v108, v96, v97
	ds_bpermute_b32 v110, v209, v108
	v_bfe_u32 v0, v240, 1, 1
	s_waitcnt lgkmcnt(0)
	v_max_f32_e32 v108, v108, v110
	v_cmp_eq_u32_e64 s[2:3], 0, v0
	s_nop 1
	v_cndmask_b32_e64 v0, v108, v196, s[2:3]
	v_max_f32_e32 v116, v117, v0
	v_sub_f32_e32 v0, v117, v116
	v_exp_f32_e32 v108, v0
	s_nop 0
	v_cmp_neq_f32_e32 vcc, 1.0, v108
	s_cbranch_vccz .LBB0_1173
	v_pk_mul_f32 v[32:33], v[32:33], v[108:109] op_sel_hi:[1,0]
	v_pk_mul_f32 v[30:31], v[30:31], v[108:109] op_sel_hi:[1,0]
	v_pk_mul_f32 v[28:29], v[28:29], v[108:109] op_sel_hi:[1,0]
	v_pk_mul_f32 v[26:27], v[26:27], v[108:109] op_sel_hi:[1,0]
	v_pk_mul_f32 v[24:25], v[24:25], v[108:109] op_sel_hi:[1,0]
	v_pk_mul_f32 v[22:23], v[22:23], v[108:109] op_sel_hi:[1,0]
	v_pk_mul_f32 v[20:21], v[20:21], v[108:109] op_sel_hi:[1,0]
	v_pk_mul_f32 v[18:19], v[18:19], v[108:109] op_sel_hi:[1,0]
	v_pk_mul_f32 v[16:17], v[16:17], v[108:109] op_sel_hi:[1,0]
	v_pk_mul_f32 v[14:15], v[14:15], v[108:109] op_sel_hi:[1,0]
	v_pk_mul_f32 v[12:13], v[12:13], v[108:109] op_sel_hi:[1,0]
	v_pk_mul_f32 v[10:11], v[10:11], v[108:109] op_sel_hi:[1,0]
	v_pk_mul_f32 v[8:9], v[8:9], v[108:109] op_sel_hi:[1,0]
	v_pk_mul_f32 v[6:7], v[6:7], v[108:109] op_sel_hi:[1,0]
	v_pk_mul_f32 v[4:5], v[4:5], v[108:109] op_sel_hi:[1,0]
	v_pk_mul_f32 v[2:3], v[2:3], v[108:109] op_sel_hi:[1,0]

.LBB0_1175:
	s_add_i32 s2, s43, 1
	s_cmp_lg_u32 s43, 5
	s_cselect_b32 s43, s2, 0
	s_add_i32 s42, s42, 2
	v_alignbit_b32 v240, v241, v240, 2
	v_lshrrev_b32_e32 v241, 2, v241
	s_addk_i32 s44, 0x80
	s_cmp_le_i32 s42, s68
	s_cbranch_scc1 .LBB0_1150
	s_branch .LBB0_1177
